# FFT small-path stage 1: the 16 KB twiddle table is copied to LDS once per phase by LDS-DMA and the per-iteration twiddle fetches use ds_read_b64 instead of global loads (short, fully covered latency)
# baseline (speedup 1.0000x reference)
.LBB0_538:
	s_andn2_b64 vcc, exec, s[16:17]
	s_cbranch_vccnz .Lfft_arrive
	v_and_b32_e32 v83, 15, v82
	v_ashrrev_i32_e32 v87, 4, v82
	v_lshlrev_b32_e64 v110, 11, s0
	v_lshl_or_b32 v0, v83, 7, v110
	v_lshlrev_b32_e32 v111, 3, v87
	v_add_u32_e32 v0, v0, v111
	v_ashrrev_i32_e32 v2, 3, v0
	s_nop 0
	v_add_u32_e32 v4, 32, v0
	v_add_u32_e32 v10, 64, v0
	v_add_u32_e32 v0, 0x60, v0
	v_ashrrev_i32_e32 v4, 3, v4
	v_ashrrev_i32_e32 v10, 3, v10
	v_ashrrev_i32_e32 v12, 3, v0
	s_add_u32 s16, s40, 0x2610000
	v_ashrrev_i32_e32 v3, 31, v2
	v_ashrrev_i32_e32 v5, 31, v4
	s_waitcnt lgkmcnt(0)
	v_ashrrev_i32_e32 v11, 31, v10
	v_ashrrev_i32_e32 v13, 31, v12
	s_addc_u32 s17, s41, 0
	v_lshlrev_b64 v[50:51], 4, v[2:3]
	v_lshlrev_b64 v[42:43], 4, v[4:5]
	v_lshlrev_b64 v[34:35], 4, v[10:11]
	v_lshlrev_b64 v[26:27], 4, v[12:13]
	v_lshl_add_u64 v[2:3], s[16:17], 0, v[50:51]
	v_lshl_add_u64 v[6:7], s[16:17], 0, v[42:43]
	v_lshl_add_u64 v[10:11], s[16:17], 0, v[34:35]
	v_lshl_add_u64 v[14:15], s[16:17], 0, v[26:27]
	s_add_u32 s16, s40, 0x2600000
	s_addc_u32 s17, s41, 0
	s_add_u32 s20, s40, 0x2608000
	s_addc_u32 s21, s41, 0
	v_lshl_add_u64 v[28:29], s[20:21], 0, v[26:27]
	v_lshl_add_u64 v[30:31], s[16:17], 0, v[26:27]
	v_lshl_add_u64 v[36:37], s[20:21], 0, v[34:35]
	v_lshl_add_u64 v[38:39], s[16:17], 0, v[34:35]
	v_lshl_add_u64 v[44:45], s[20:21], 0, v[42:43]
	v_lshl_add_u64 v[46:47], s[16:17], 0, v[42:43]
	v_lshl_add_u64 v[52:53], s[20:21], 0, v[50:51]
	v_lshl_add_u64 v[54:55], s[16:17], 0, v[50:51]
	global_load_dwordx4 v[2:5], v[2:3], off
	s_nop 0
	global_load_dwordx4 v[6:9], v[6:7], off
	s_nop 0
	global_load_dwordx4 v[10:13], v[10:11], off
	s_nop 0
	global_load_dwordx4 v[14:17], v[14:15], off
	s_nop 0
	global_load_dwordx4 v[26:29], v[28:29], off
	s_nop 0
	global_load_dwordx4 v[30:33], v[30:31], off
	s_nop 0
	global_load_dwordx4 v[34:37], v[36:37], off
	s_nop 0
	global_load_dwordx4 v[38:41], v[38:39], off
	s_nop 0
	global_load_dwordx4 v[42:45], v[44:45], off
	s_nop 0
	global_load_dwordx4 v[46:49], v[46:47], off
	s_nop 0
	global_load_dwordx4 v[50:53], v[52:53], off
	s_nop 0
	global_load_dwordx4 v[54:57], v[54:55], off
	v_lshl_add_u32 v0, v83, 5, v111
	v_ashrrev_i32_e32 v88, 3, v0
	v_ashrrev_i32_e32 v89, 31, v88
	v_lshl_add_u64 v[88:89], v[88:89], 4, s[40:41]
	s_mov_b64 s[16:17], 0x2618000
	v_cmp_gt_i32_e32 vcc, 2, v87
	v_mov_b32_e32 v0, 0x8800
	v_bfe_u32 v105, v138, 1, 7
	v_lshlrev_b32_e32 v95, 4, v138
	v_lshl_add_u64 v[92:93], v[88:89], 0, s[16:17]
	s_mov_b64 s[16:17], 0x2618400
	v_cndmask_b32_e64 v115, v0, 0, vcc
	v_lshlrev_b32_e32 v0, 5, v105
	v_lshl_add_u64 v[96:97], v[88:89], 0, s[16:17]
	v_lshl_add_u64 v[88:89], s[42:43], 0, v[0:1]
	v_and_b32_e32 v0, 16, v95
	v_ashrrev_i32_e32 v85, 11, v138
	v_bfe_u32 v106, v138, 4, 7
	v_lshl_add_u64 v[98:99], v[88:89], 0, v[0:1]
	v_mul_i32_i24_e32 v85, 0x8800, v85
	v_mul_u32_u24_e32 v88, 0x110, v106
	v_add_u32_e32 v107, 0x200, v138
	v_add3_u32 v119, 0, v85, v88
	v_ashrrev_i32_e32 v85, 11, v107
	v_bfe_u32 v109, v107, 4, 7
	v_mul_i32_i24_e32 v85, 0x8800, v85
	v_mul_u32_u24_e32 v88, 0x110, v109
	v_add_u32_e32 v121, 0x400, v138
	v_add3_u32 v120, 0, v85, v88
	v_ashrrev_i32_e32 v85, 11, v121
	v_bfe_u32 v123, v121, 4, 7
	v_mul_i32_i24_e32 v85, 0x8800, v85
	v_mul_u32_u24_e32 v88, 0x110, v123
	v_add_u32_e32 v125, 0x600, v138
	v_add3_u32 v124, 0, v85, v88
	v_ashrrev_i32_e32 v85, 11, v125
	v_bfe_u32 v127, v125, 4, 7
	v_mul_i32_i24_e32 v85, 0x8800, v85
	v_mul_u32_u24_e32 v88, 0x110, v127
	v_add_u32_e32 v129, 0x800, v138
	v_add3_u32 v128, 0, v85, v88
	v_ashrrev_i32_e32 v85, 11, v129
	v_bfe_u32 v131, v129, 4, 7
	v_mul_i32_i24_e32 v85, 0x8800, v85
	v_mul_u32_u24_e32 v88, 0x110, v131
	v_add_u32_e32 v133, 0xa00, v138
	v_add3_u32 v132, 0, v85, v88
	v_ashrrev_i32_e32 v85, 11, v133
	v_bfe_u32 v135, v133, 4, 7
	v_mul_i32_i24_e32 v85, 0x8800, v85
	v_mul_u32_u24_e32 v88, 0x110, v135
	v_add_u32_e32 v137, 0xc00, v138
	v_add3_u32 v136, 0, v85, v88
	v_ashrrev_i32_e32 v85, 11, v137
	v_bfe_u32 v167, v137, 4, 7
	s_add_u32 s44, s40, 0x2619000
	v_mul_i32_i24_e32 v85, 0x8800, v85
	v_mul_u32_u24_e32 v88, 0x110, v167
	v_add_u32_e32 v173, 0xe00, v138
	s_addc_u32 s45, s41, 0
	v_lshlrev_b32_e32 v113, 9, v87
	v_add3_u32 v204, 0, v85, v88
	v_ashrrev_i32_e32 v85, 11, v173
	v_bfe_u32 v171, v173, 4, 7
	s_add_u32 s46, s40, 0x2639000
	v_or_b32_e32 v84, v113, v83
	v_mul_i32_i24_e32 v85, 0x8800, v85
	v_mul_u32_u24_e32 v88, 0x110, v171
	s_addc_u32 s47, s41, 0
	v_add3_u32 v205, 0, v85, v88
	v_ashrrev_i32_e32 v85, 31, v84
	v_lshl_add_u64 v[100:101], v[84:85], 3, s[46:47]
	v_ashrrev_i32_e32 v85, 3, v138
	v_and_b32_e32 v145, 0xffffff00, v85
	v_ashrrev_i32_e32 v85, 3, v107
	v_and_b32_e32 v149, 0xffffff00, v85
	v_ashrrev_i32_e32 v85, 3, v121
	v_and_b32_e32 v153, 0xffffff00, v85
	v_ashrrev_i32_e32 v85, 3, v125
	v_and_b32_e32 v157, 0xffffff00, v85
	v_lshlrev_b32_e32 v85, 3, v129
	v_lshrrev_b32_e32 v126, 4, v125
	v_and_b32_e32 v160, 0x780, v85
	v_ashrrev_i32_e32 v85, 3, v129
	v_lshlrev_b32_e64 v114, 4, s0
	v_and_b32_e32 v116, 8, v111
	v_bfe_u32 v117, v82, 2, 2
	v_lshlrev_b32_e64 v118, 5, s0
	v_bfe_u32 v154, v126, 4, 3
	v_and_b32_e32 v161, 0xffffff00, v85
	v_lshlrev_b32_e32 v85, 3, v133
	v_mul_u32_u24_e32 v126, 0x110, v83
	s_mov_b32 s100, 0x22000
	s_lshl_b32 s98, s0, 11
	v_lshlrev_b32_e32 v248, 4, v233
	s_add_i32 s98, s98, 0x22000
	v_add_u32_e32 v248, s98, v248
	v_subrev_u32_e32 v248, 0x22000, v248
	s_mov_b32 m0, s98
	v_add_u32_e32 v249, 0x400, v248
	global_load_lds_dwordx4 v248, s[46:47]
	s_add_i32 m0, s98, 0x400
	s_nop 0
	global_load_lds_dwordx4 v249, s[46:47]
	s_waitcnt vmcnt(0)
	v_and_b32_e32 v164, 0x780, v85
	v_ashrrev_i32_e32 v85, 3, v133
	v_add3_u32 v180, v126, v118, v111
	v_or3_b32 v111, v114, v116, v117
	s_movk_i32 s10, 0x110
	v_lshlrev_b32_e32 v82, 3, v82
	v_lshlrev_b32_e32 v91, 2, v87
	v_and_b32_e32 v165, 0xffffff00, v85
	v_lshlrev_b32_e32 v85, 3, v137
	v_mul_lo_u32 v111, v111, s10
	v_and_b32_e32 v82, 24, v82
	s_movk_i32 s10, 0x880
	v_or_b32_e32 v139, 16, v84
	v_add_lshl_u32 v141, v91, v114, 7
	v_and_b32_e32 v168, 0x780, v85
	v_ashrrev_i32_e32 v85, 3, v137
	v_add3_u32 v181, v115, v111, v82
	v_or_b32_e32 v182, 0x190, v84
	v_mul_lo_u32 v84, v87, s10
	v_mul_u32_u24_e32 v111, 0x110, v117
	v_or_b32_e32 v88, v141, v83
	v_and_b32_e32 v169, 0xffffff00, v85
	v_lshlrev_b32_e32 v85, 3, v173
	v_add3_u32 v183, v84, v111, v82
	v_add_u32_e32 v82, v110, v113
	v_lshrrev_b32_e32 v104, 4, v138
	v_lshrrev_b32_e32 v122, 4, v121
	v_ashrrev_i32_e32 v89, 31, v88
	v_and_b32_e32 v172, 0x780, v85
	v_ashrrev_i32_e32 v85, 3, v173
	v_ashrrev_i32_e32 v176, 8, v138
	v_ashrrev_i32_e32 v177, 8, v107
	v_ashrrev_i32_e32 v178, 8, v121
	v_ashrrev_i32_e32 v179, 8, v125
	v_or_b32_e32 v184, v82, v83
	v_lshlrev_b32_e32 v82, 10, v87
	v_lshlrev_b32_e32 v90, 3, v138
	v_lshrrev_b32_e32 v108, 4, v107
	v_lshrrev_b32_e32 v170, 4, v173
	v_lshl_add_u64 v[102:103], v[88:89], 3, s[44:45]
	v_bfe_u32 v142, v104, 4, 3
	v_lshlrev_b32_e32 v147, 7, v109
	v_lshlrev_b32_e32 v104, 3, v107
	v_bfe_u32 v150, v122, 4, 3
	v_and_b32_e32 v173, 0xffffff00, v85
	v_lshlrev_b32_e32 v85, 5, v176
	v_lshlrev_b32_e32 v88, 8, v105
	v_lshlrev_b32_e32 v89, 5, v177
	v_lshlrev_b32_e32 v122, 4, v107
	v_lshlrev_b32_e32 v107, 5, v178
	v_lshlrev_b32_e32 v109, 5, v179
	v_lshl_add_u32 v82, s0, 12, v82
	v_and_b32_e32 v112, 0xf0, v95
	v_and_b32_e32 v86, 0x78, v90
	v_lshrrev_b32_e32 v130, 4, v129
	v_lshrrev_b32_e32 v134, 4, v133
	v_lshrrev_b32_e32 v166, 4, v137
	v_lshlrev_b32_e32 v143, 7, v106
	v_bfe_u32 v146, v108, 4, 3
	v_lshlrev_b32_e32 v151, 7, v123
	v_lshlrev_b32_e32 v106, 3, v121
	v_lshlrev_b32_e32 v108, 3, v125
	v_add3_u32 v85, 0, v85, v88
	v_add3_u32 v89, 0, v89, v88
	v_add3_u32 v123, 0, v107, v88
	v_lshlrev_b32_e32 v121, 4, v121
	v_add3_u32 v88, 0, v109, v88
	v_lshlrev_b32_e32 v125, 4, v125
	v_lshl_or_b32 v82, v83, 1, v82
	v_or_b32_e32 v140, 16, v83
	v_and_b32_e32 v144, 0x780, v90
	v_and_b32_e32 v148, 0x780, v104
	v_and_b32_e32 v152, 0x780, v106
	v_lshlrev_b32_e32 v155, 7, v127
	v_and_b32_e32 v156, 0x780, v108
	v_bfe_u32 v158, v130, 4, 3
	v_lshlrev_b32_e32 v159, 7, v131
	v_bfe_u32 v162, v134, 4, 3
	v_lshlrev_b32_e32 v163, 7, v135
	v_bfe_u32 v166, v166, 4, 3
	v_lshlrev_b32_e32 v167, 7, v167
	v_bfe_u32 v170, v170, 4, 3
	v_lshlrev_b32_e32 v171, 7, v171
	v_or_b32_e32 v174, 0x80, v141
	v_or_b32_e32 v175, 0x180, v141
	v_ashrrev_i32_e32 v91, 31, v90
	v_ashrrev_i32_e32 v105, 31, v104
	v_ashrrev_i32_e32 v107, 31, v106
	v_ashrrev_i32_e32 v109, 31, v108
	v_add_u32_e32 v185, 0, v183
	v_add_u32_e32 v193, 0, v82
	v_add_u32_e32 v198, v119, v112
	v_add_u32_e32 v199, v120, v112
	v_add_u32_e32 v200, v124, v112
	v_add_u32_e32 v201, v128, v112
	v_add_u32_e32 v202, v132, v112
	v_add_u32_e32 v203, v136, v112
	v_add_u32_e32 v204, v204, v112
	v_add_u32_e32 v205, v205, v112
	v_lshlrev_b32_e32 v110, 1, v86
	v_add_u32_e32 v206, v85, v0
	v_add_u32_e32 v207, v89, v0
	v_add_u32_e32 v208, 0, v122
	v_add_u32_e32 v209, v123, v0
	v_add_u32_e32 v210, 0, v121
	v_add_u32_e32 v211, v88, v0
	v_add_u32_e32 v212, 0, v125
	s_branch .LBB0_541

.LBB0_551:
	v_add_u32_e32 v213, 0, v0
	ds_read_b64_tr_b16 v[214:215], v213
	ds_read_b64_tr_b16 v[216:217], v213 offset:1088
	s_waitcnt lgkmcnt(2)
	v_mov_b32_e32 v222, v126
	s_nop 0
	v_mov_b32_e32 v223, v124
	v_mov_b32_e32 v124, v127
	v_add_u32_e32 v130, 0xfffffe80, v120
	s_waitcnt vmcnt(1) lgkmcnt(0)
	v_mfma_f32_16x16x32_f16 v[218:221], v[82:85], v[214:217], 0
	s_nop 0
	v_lshl_add_u32 v130, v130, 3, s100
	v_ashrrev_i32_e32 v121, 31, v120
	s_waitcnt vmcnt(0)
	v_mfma_f32_16x16x32_f16 v[214:217], v[86:89], v[214:217], 0
	ds_read_b64 v[134:135], v130
	ds_read_b64 v[132:133], v130 offset:1024
	ds_read_b64 v[136:137], v130 offset:3072
	ds_read_b64 v[130:131], v130 offset:2048
	s_nop 1
	v_pk_mul_f32 v[126:127], v[124:125], v[214:215]
	v_pk_mul_f32 v[214:215], v[222:223], v[214:215]
	v_pk_fma_f32 v[126:127], v[222:223], v[218:219], v[126:127] neg_lo:[0,0,1] neg_hi:[0,0,1]
	v_pk_fma_f32 v[124:125], v[124:125], v[218:219], v[214:215]
	v_mov_b32_e32 v215, v128
	v_mov_b32_e32 v128, v123
	v_mov_b32_e32 v214, v122
	v_pk_mul_f32 v[122:123], v[128:129], v[216:217]
	v_cvt_pk_f16_f32 v126, v126, v127
	v_pk_fma_f32 v[122:123], v[214:215], v[220:221], v[122:123] neg_lo:[0,0,1] neg_hi:[0,0,1]
	v_add_u32_e32 v121, 0, v111
	v_cvt_pk_f16_f32 v127, v122, v123
	v_pk_mul_f32 v[122:123], v[214:215], v[216:217]
	s_min_i32 s10, s1, 6
	v_pk_fma_f32 v[122:123], v[128:129], v[220:221], v[122:123]
	v_cvt_pk_f16_f32 v124, v124, v125
	v_cvt_pk_f16_f32 v125, v122, v123
	v_add_u32_e32 v122, 0x11000, v121
	v_lshl_add_u32 v128, s10, 4, v139
	ds_write_b64 v122, v[126:127]
	v_add_u32_e32 v122, 0x19800, v121
	s_nop 0
	ds_write_b64 v122, v[124:125]
	v_lshl_add_u32 v122, v128, 3, s100
	s_nop 0
	s_nop 0
	ds_read_b64_tr_b16 v[214:215], v213 offset:32
	ds_read_b64_tr_b16 v[216:217], v213 offset:1120
	s_waitcnt lgkmcnt(0)
	ds_read_b64 v[126:127], v122
	ds_read_b64 v[124:125], v122 offset:1024
	ds_read_b64 v[128:129], v122 offset:3072
	ds_read_b64 v[122:123], v122 offset:2048
	v_mfma_f32_16x16x32_f16 v[218:221], v[82:85], v[214:217], 0
	s_add_i32 s1, s1, 2
	v_add_u32_e32 v111, 0x2200, v111
	v_add_u32_e32 v0, 64, v0
	v_mfma_f32_16x16x32_f16 v[214:217], v[86:89], v[214:217], 0
	v_add_u32_e32 v120, 32, v120
	s_cmp_lg_u32 s1, 9
	s_nop 0
	v_mov_b32_e32 v222, v134
	s_nop 0
	v_mov_b32_e32 v223, v132
	v_mov_b32_e32 v132, v135
	s_nop 0
	v_pk_mul_f32 v[134:135], v[132:133], v[214:215]
	v_pk_mul_f32 v[214:215], v[222:223], v[214:215]
	v_pk_fma_f32 v[134:135], v[222:223], v[218:219], v[134:135] neg_lo:[0,0,1] neg_hi:[0,0,1]
	v_pk_fma_f32 v[132:133], v[132:133], v[218:219], v[214:215]
	s_nop 0
	v_mov_b32_e32 v215, v136
	v_mov_b32_e32 v136, v131
	v_mov_b32_e32 v214, v130
	v_pk_mul_f32 v[130:131], v[136:137], v[216:217]
	v_cvt_pk_f16_f32 v134, v134, v135
	v_pk_fma_f32 v[130:131], v[214:215], v[220:221], v[130:131] neg_lo:[0,0,1] neg_hi:[0,0,1]
	v_cvt_pk_f16_f32 v132, v132, v133
	v_cvt_pk_f16_f32 v135, v130, v131
	v_pk_mul_f32 v[130:131], v[214:215], v[216:217]
	s_nop 0
	v_pk_fma_f32 v[130:131], v[136:137], v[220:221], v[130:131]
	s_nop 0
	v_cvt_pk_f16_f32 v133, v130, v131
	v_add_u32_e32 v130, 0x12100, v121
	v_add_u32_e32 v121, 0x1a900, v121
	ds_write_b64 v130, v[134:135]
	ds_write_b64 v121, v[132:133]
	s_cbranch_scc1 .LBB0_551
	s_mov_b64 s[48:49], 0
